# v8 + NSA sliding-window loop P.V block: row-sum adds and bf16 packing moved into the P.V MFMA gaps, V fragments double-buffered
# speedup vs baseline: 1.0011x; 1.0011x over previous
; __device__ __forceinline__ float fast_exp2(float x) { return __builtin_amdgcn_exp2f(x); }
; __device__ __forceinline__ float xhalf_max(float x) { auto rr = __builtin_amdgcn_permlane32_swap(__float_as_uint(x), __float_as_uint(x), false, false); return fmaxf(__uint_as_float(rr[0]), __uint_as_float(rr[1])); }
; template <int D, int DV, int MODE, bool HASBIAS, bool JOINT, bool DEFER, class KA, class VA, class PF, class BF, class VF, class NM, class WS, class CB> ...
;     ...
;                     float mx0 = fmaxf(fmaxf(s[0], s[1]), s[2]), mx1 = fmaxf(fmaxf(s[3], s[4]), s[5]);
;                     mx0 = fmaxf(fmaxf(mx0, s[6]), s[7]); mx1 = fmaxf(fmaxf(mx1, s[8]), s[9]); mx0 = fmaxf(fmaxf(mx0, s[10]), s[11]); mx1 = fmaxf(fmaxf(mx1, s[12]), s[13]);
;                     float mx = fmaxf(fmaxf(mx0, mx1), fmaxf(s[14], s[15]));
;                     mx = xhalf_max(mx);
;                     const bool grow = __any(mx > m + RESC_THR);
;                     const float mn = grow ? fmaxf(m, mx) : m; float sum = 0.f;
;                     if (masked) {
; #pragma unroll
;                         for (int v = 0; v < 16; ++v) { const float p = s[v] > -1e29f ? fast_exp2(s[v] - mn) : 0.f; s[v] = p; sum += p; }
;                     } else {
; #pragma unroll
;                         for (int v = 0; v < 16; ++v) { const float p = fast_exp2(s[v] - mn); s[v] = p; sum += p; }
;                     }
.LBB0_907:
	v_max3_f32 v1, v126, v127, v102
	v_max3_f32 v2, v103, v100, v101
	v_max3_f32 v1, v1, v98, v99
	v_max3_f32 v2, v2, v96, v97
	v_max_f32_e32 v36, v51, v51
	v_max_f32_e32 v37, v50, v50
	v_max3_f32 v1, v1, v94, v95
	v_max3_f32 v2, v2, v92, v93
	v_max_f32_e32 v36, v37, v36
	v_max3_f32 v1, v1, v2, v36
	v_mov_b32_e32 v2, v1
	s_nop 1
	v_permlane32_swap_b32_e32 v1, v2
	v_max_f32_e32 v2, v2, v2
	v_max_f32_e32 v1, v1, v1
	v_max_f32_e32 v1, v1, v2
	v_add_f32_e32 v2, 0x40c00000, v140
	v_cmp_gt_f32_e32 vcc, v1, v2
	s_cmp_lg_u64 vcc, 0
	s_cselect_b64 s[8:9], -1, 0
	s_cmp_eq_u64 vcc, 0
	v_max_f32_e32 v2, v140, v140
	s_cselect_b64 vcc, -1, 0
	v_max_f32_e32 v142, v2, v1
	v_cndmask_b32_e32 v141, v142, v140, vcc
	v_sub_f32_e32 v1, v126, v141
	v_sub_f32_e32 v2, v127, v141
	v_sub_f32_e32 v36, v102, v141
	v_sub_f32_e32 v37, v103, v141
	v_sub_f32_e32 v38, v100, v141
	v_sub_f32_e32 v39, v101, v141
	v_sub_f32_e32 v40, v98, v141
	v_sub_f32_e32 v41, v99, v141
	v_sub_f32_e32 v42, v96, v141
	v_sub_f32_e32 v43, v97, v141
	v_sub_f32_e32 v143, v94, v141
	v_sub_f32_e32 v144, v95, v141
	v_sub_f32_e32 v145, v92, v141
	v_sub_f32_e32 v146, v93, v141
	v_sub_f32_e32 v147, v50, v141
	v_sub_f32_e32 v148, v51, v141
	v_exp_f32_e32 v48, v1
	v_exp_f32_e32 v1, v2
	v_exp_f32_e32 v2, v36
	v_exp_f32_e32 v49, v37
	v_exp_f32_e32 v46, v38
	v_exp_f32_e32 v47, v39
	v_exp_f32_e32 v44, v40
	v_exp_f32_e32 v45, v41
	v_exp_f32_e32 v42, v42
	v_exp_f32_e32 v43, v43
	v_exp_f32_e32 v40, v143
	v_exp_f32_e32 v41, v144
	v_exp_f32_e32 v38, v145
	v_exp_f32_e32 v39, v146
	v_exp_f32_e32 v36, v147
	v_exp_f32_e32 v37, v148
	s_mov_b64 s[16:17], -1
	s_andn2_b64 vcc, exec, s[10:11]
	s_cbranch_vccnz .LBB0_957
	s_cbranch_execz .LBB0_958

; __device__ __forceinline__ unsigned cvt_pk_bf16(float lo, float hi) { unsigned r; asm volatile("v_cvt_pk_bf16_f32 %0, %1, %2" : "=v"(r) : "v"(lo), "v"(hi)); return r; }
; #define LAS __attribute__((address_space(3)))
; template <int DV32>
; __device__ __forceinline__ void pv_sub(f32x16 (&o)[DV32], const LAS unsigned char* Vt, int vs, int sub, const f32x16& p, int r32, int hi) {
;     ...
;     for (int kb = 0; kb < 2; ++kb) {
;         u32x4 pw; pw.x = cvt_pk_bf16(p[8 * kb + 0], p[8 * kb + 1]); pw.y = cvt_pk_bf16(p[8 * kb + 2], p[8 * kb + 3]); pw.z = cvt_pk_bf16(p[8 * kb + 4], p[8 * kb + 5]); pw.w = cvt_pk_bf16(p[8 * kb + 6], p[8 * kb + 7]);
;         const bf16x8 pf = __builtin_bit_cast(bf16x8, pw);
; #pragma unroll
;         for (int i = 0; i < DV32; ++i) {
;             const bf16x8 vf = *(const LAS bf16x8*)(Vt + (32 * i + r32) * vs + sub * 64 + kb * 32 + hi * 16);
;             o[i] = __builtin_amdgcn_mfma_f32_32x32x16_bf16(vf, pf, o[i], 0, 0, 0);
;         }
; template <int D, int DV, int MODE, bool HASBIAS, bool JOINT, bool DEFER, class KA, class VA, class PF, class BF, class VF, class NM, class WS, class CB> ...
;     ...
;                     l += sum; m = mn;
;                     if (MODE == 0) pv_sub<DV / 32>(o, curv, VS, sub, s, r32, hi);
.LBB0_911:
	v_cvt_pk_bf16_f32 v92, v48, v1
	v_cvt_pk_bf16_f32 v93, v2, v49
	v_add_f32_e32 v143, 0, v48
	v_add_f32_e32 v143, v1, v143
	v_add_f32_e32 v143, v2, v143
	v_add_f32_e32 v143, v49, v143
	v_add_u32_e32 v1, v167, v164
	ds_read_b128 v[100:103], v1 offset:18432
	ds_read_b128 v[144:147], v1 offset:23040
	v_cvt_pk_bf16_f32 v94, v46, v47
	v_cvt_pk_bf16_f32 v95, v44, v45
	v_add_f32_e32 v143, v46, v143
	v_add_f32_e32 v143, v47, v143
	v_mov_b32_e32 v140, v141
	s_waitcnt lgkmcnt(1)
	v_mfma_f32_32x32x16_bf16 v[4:19], v[100:103], v[92:95], v[4:19]
	ds_read_b128 v[100:103], v1 offset:18464
	v_add_f32_e32 v143, v44, v143
	v_add_f32_e32 v143, v45, v143
	v_cvt_pk_bf16_f32 v96, v42, v43
	v_cvt_pk_bf16_f32 v97, v40, v41
	s_waitcnt lgkmcnt(1)
	v_mfma_f32_32x32x16_bf16 v[20:35], v[144:147], v[92:95], v[20:35]
	ds_read_b128 v[144:147], v1 offset:23072
	v_cvt_pk_bf16_f32 v98, v38, v39
	v_cvt_pk_bf16_f32 v99, v36, v37
	v_add_f32_e32 v143, v42, v143
	v_add_f32_e32 v143, v43, v143
	v_add_f32_e32 v143, v40, v143
	v_add_f32_e32 v143, v41, v143
	s_waitcnt lgkmcnt(1)
	v_mfma_f32_32x32x16_bf16 v[4:19], v[100:103], v[96:99], v[4:19]
	v_add_f32_e32 v143, v38, v143
	v_add_f32_e32 v143, v39, v143
	v_add_f32_e32 v143, v36, v143
	v_add_f32_e32 v143, v37, v143
	v_add_f32_e32 v139, v143, v139
	s_waitcnt lgkmcnt(0)
	v_mfma_f32_32x32x16_bf16 v[20:35], v[144:147], v[96:99], v[20:35]

; __device__ __forceinline__ unsigned cvt_pk_bf16(float lo, float hi) { unsigned r; asm volatile("v_cvt_pk_bf16_f32 %0, %1, %2" : "=v"(r) : "v"(lo), "v"(hi)); return r; }
; #define LAS __attribute__((address_space(3)))
; template <int DV32>
; __device__ __forceinline__ void pv_sub(f32x16 (&o)[DV32], const LAS unsigned char* Vt, int vs, int sub, const f32x16& p, int r32, int hi) {
;     ...
;     for (int kb = 0; kb < 2; ++kb) {
;         u32x4 pw; pw.x = cvt_pk_bf16(p[8 * kb + 0], p[8 * kb + 1]); pw.y = cvt_pk_bf16(p[8 * kb + 2], p[8 * kb + 3]); pw.z = cvt_pk_bf16(p[8 * kb + 4], p[8 * kb + 5]); pw.w = cvt_pk_bf16(p[8 * kb + 6], p[8 * kb + 7]);
;         const bf16x8 pf = __builtin_bit_cast(bf16x8, pw);
; #pragma unroll
;         for (int i = 0; i < DV32; ++i) {
;             const bf16x8 vf = *(const LAS bf16x8*)(Vt + (32 * i + r32) * vs + sub * 64 + kb * 32 + hi * 16);
;             o[i] = __builtin_amdgcn_mfma_f32_32x32x16_bf16(vf, pf, o[i], 0, 0, 0);
;         }
; template <int D, int DV, int MODE, bool HASBIAS, bool JOINT, bool DEFER, class KA, class VA, class PF, class BF, class VF, class NM, class WS, class CB> ...
;     ...
;                     l += sum; m = mn;
;                     if (MODE == 0) pv_sub<DV / 32>(o, curv, VS, sub, s, r32, hi);
.LBB0_920:
	v_cvt_pk_bf16_f32 v92, v48, v1
	v_cvt_pk_bf16_f32 v93, v2, v49
	v_add_f32_e32 v143, 0, v48
	v_add_f32_e32 v143, v1, v143
	v_add_f32_e32 v143, v2, v143
	v_add_f32_e32 v143, v49, v143
	v_add_u32_e32 v1, v167, v164
	ds_read_b128 v[100:103], v1 offset:18496
	ds_read_b128 v[144:147], v1 offset:23104
	v_cvt_pk_bf16_f32 v94, v46, v47
	v_cvt_pk_bf16_f32 v95, v44, v45
	v_add_f32_e32 v143, v46, v143
	v_add_f32_e32 v143, v47, v143
	v_mov_b32_e32 v140, v141
	s_waitcnt lgkmcnt(1)
	v_mfma_f32_32x32x16_bf16 v[4:19], v[100:103], v[92:95], v[4:19]
	ds_read_b128 v[100:103], v1 offset:18528
	v_add_f32_e32 v143, v44, v143
	v_add_f32_e32 v143, v45, v143
	v_cvt_pk_bf16_f32 v96, v42, v43
	v_cvt_pk_bf16_f32 v97, v40, v41
	s_waitcnt lgkmcnt(1)
	v_mfma_f32_32x32x16_bf16 v[20:35], v[144:147], v[92:95], v[20:35]
	ds_read_b128 v[144:147], v1 offset:23136
	v_cvt_pk_bf16_f32 v98, v38, v39
	v_cvt_pk_bf16_f32 v99, v36, v37
	v_add_f32_e32 v143, v42, v143
	v_add_f32_e32 v143, v43, v143
	v_add_f32_e32 v143, v40, v143
	v_add_f32_e32 v143, v41, v143
	s_waitcnt lgkmcnt(1)
	v_mfma_f32_32x32x16_bf16 v[4:19], v[100:103], v[96:99], v[4:19]
	v_add_f32_e32 v143, v38, v143
	v_add_f32_e32 v143, v39, v143
	v_add_f32_e32 v143, v36, v143
	v_add_f32_e32 v143, v37, v143
	v_add_f32_e32 v139, v143, v139
	s_waitcnt lgkmcnt(0)
	v_mfma_f32_32x32x16_bf16 v[20:35], v[144:147], v[96:99], v[20:35]

; __device__ __forceinline__ unsigned cvt_pk_bf16(float lo, float hi) { unsigned r; asm volatile("v_cvt_pk_bf16_f32 %0, %1, %2" : "=v"(r) : "v"(lo), "v"(hi)); return r; }
; #define LAS __attribute__((address_space(3)))
; template <int DV32>
; __device__ __forceinline__ void pv_sub(f32x16 (&o)[DV32], const LAS unsigned char* Vt, int vs, int sub, const f32x16& p, int r32, int hi) {
;     ...
;     for (int kb = 0; kb < 2; ++kb) {
;         u32x4 pw; pw.x = cvt_pk_bf16(p[8 * kb + 0], p[8 * kb + 1]); pw.y = cvt_pk_bf16(p[8 * kb + 2], p[8 * kb + 3]); pw.z = cvt_pk_bf16(p[8 * kb + 4], p[8 * kb + 5]); pw.w = cvt_pk_bf16(p[8 * kb + 6], p[8 * kb + 7]);
;         const bf16x8 pf = __builtin_bit_cast(bf16x8, pw);
; #pragma unroll
;         for (int i = 0; i < DV32; ++i) {
;             const bf16x8 vf = *(const LAS bf16x8*)(Vt + (32 * i + r32) * vs + sub * 64 + kb * 32 + hi * 16);
;             o[i] = __builtin_amdgcn_mfma_f32_32x32x16_bf16(vf, pf, o[i], 0, 0, 0);
;         }
; template <int D, int DV, int MODE, bool HASBIAS, bool JOINT, bool DEFER, class KA, class VA, class PF, class BF, class VF, class NM, class WS, class CB> ...
;     ...
;                     l += sum; m = mn;
;                     if (MODE == 0) pv_sub<DV / 32>(o, curv, VS, sub, s, r32, hi);
.LBB0_942:
	v_cvt_pk_bf16_f32 v92, v48, v1
	v_cvt_pk_bf16_f32 v93, v2, v49
	v_add_f32_e32 v143, 0, v48
	v_add_f32_e32 v143, v1, v143
	v_add_f32_e32 v143, v2, v143
	v_add_f32_e32 v143, v49, v143
	v_add_u32_e32 v1, v167, v164
	ds_read_b128 v[100:103], v1 offset:27648
	ds_read_b128 v[144:147], v1 offset:32256
	v_cvt_pk_bf16_f32 v94, v46, v47
	v_cvt_pk_bf16_f32 v95, v44, v45
	v_add_f32_e32 v143, v46, v143
	v_add_f32_e32 v143, v47, v143
	v_mov_b32_e32 v140, v141
	s_waitcnt lgkmcnt(1)
	v_mfma_f32_32x32x16_bf16 v[4:19], v[100:103], v[92:95], v[4:19]
	ds_read_b128 v[100:103], v1 offset:27680
	v_add_f32_e32 v143, v44, v143
	v_add_f32_e32 v143, v45, v143
	v_cvt_pk_bf16_f32 v96, v42, v43
	v_cvt_pk_bf16_f32 v97, v40, v41
	s_waitcnt lgkmcnt(1)
	v_mfma_f32_32x32x16_bf16 v[20:35], v[144:147], v[92:95], v[20:35]
	ds_read_b128 v[144:147], v1 offset:32288
	v_cvt_pk_bf16_f32 v98, v38, v39
	v_cvt_pk_bf16_f32 v99, v36, v37
	v_add_f32_e32 v143, v42, v143
	v_add_f32_e32 v143, v43, v143
	v_add_f32_e32 v143, v40, v143
	v_add_f32_e32 v143, v41, v143
	s_waitcnt lgkmcnt(1)
	v_mfma_f32_32x32x16_bf16 v[4:19], v[100:103], v[96:99], v[4:19]
	v_add_f32_e32 v143, v38, v143
	v_add_f32_e32 v143, v39, v143
	v_add_f32_e32 v143, v36, v143
	v_add_f32_e32 v143, v37, v143
	v_add_f32_e32 v139, v143, v139
	s_waitcnt lgkmcnt(0)
	v_mfma_f32_32x32x16_bf16 v[20:35], v[144:147], v[96:99], v[20:35]

; __device__ __forceinline__ unsigned cvt_pk_bf16(float lo, float hi) { unsigned r; asm volatile("v_cvt_pk_bf16_f32 %0, %1, %2" : "=v"(r) : "v"(lo), "v"(hi)); return r; }
; #define LAS __attribute__((address_space(3)))
; template <int DV32>
; __device__ __forceinline__ void pv_sub(f32x16 (&o)[DV32], const LAS unsigned char* Vt, int vs, int sub, const f32x16& p, int r32, int hi) {
;     ...
;     for (int kb = 0; kb < 2; ++kb) {
;         u32x4 pw; pw.x = cvt_pk_bf16(p[8 * kb + 0], p[8 * kb + 1]); pw.y = cvt_pk_bf16(p[8 * kb + 2], p[8 * kb + 3]); pw.z = cvt_pk_bf16(p[8 * kb + 4], p[8 * kb + 5]); pw.w = cvt_pk_bf16(p[8 * kb + 6], p[8 * kb + 7]);
;         const bf16x8 pf = __builtin_bit_cast(bf16x8, pw);
; #pragma unroll
;         for (int i = 0; i < DV32; ++i) {
;             const bf16x8 vf = *(const LAS bf16x8*)(Vt + (32 * i + r32) * vs + sub * 64 + kb * 32 + hi * 16);
;             o[i] = __builtin_amdgcn_mfma_f32_32x32x16_bf16(vf, pf, o[i], 0, 0, 0);
;         }
; template <int D, int DV, int MODE, bool HASBIAS, bool JOINT, bool DEFER, class KA, class VA, class PF, class BF, class VF, class NM, class WS, class CB> ...
;     ...
;                     l += sum; m = mn;
;                     if (MODE == 0) pv_sub<DV / 32>(o, curv, VS, sub, s, r32, hi);
.LBB0_951:
	v_cvt_pk_bf16_f32 v92, v48, v1
	v_cvt_pk_bf16_f32 v93, v2, v49
	v_add_f32_e32 v143, 0, v48
	v_add_f32_e32 v143, v1, v143
	v_add_f32_e32 v143, v2, v143
	v_add_f32_e32 v143, v49, v143
	v_add_u32_e32 v1, v167, v164
	ds_read_b128 v[100:103], v1 offset:27712
	ds_read_b128 v[144:147], v1 offset:32320
	v_cvt_pk_bf16_f32 v94, v46, v47
	v_cvt_pk_bf16_f32 v95, v44, v45
	v_add_f32_e32 v143, v46, v143
	v_add_f32_e32 v143, v47, v143
	v_mov_b32_e32 v140, v141
	s_waitcnt lgkmcnt(1)
	v_mfma_f32_32x32x16_bf16 v[4:19], v[100:103], v[92:95], v[4:19]
	ds_read_b128 v[100:103], v1 offset:27744
	v_add_f32_e32 v143, v44, v143
	v_add_f32_e32 v143, v45, v143
	v_cvt_pk_bf16_f32 v96, v42, v43
	v_cvt_pk_bf16_f32 v97, v40, v41
	s_waitcnt lgkmcnt(1)
	v_mfma_f32_32x32x16_bf16 v[20:35], v[144:147], v[92:95], v[20:35]
	ds_read_b128 v[144:147], v1 offset:32352
	v_cvt_pk_bf16_f32 v98, v38, v39
	v_cvt_pk_bf16_f32 v99, v36, v37
	v_add_f32_e32 v143, v42, v143
	v_add_f32_e32 v143, v43, v143
	v_add_f32_e32 v143, v40, v143
	v_add_f32_e32 v143, v41, v143
	s_waitcnt lgkmcnt(1)
	v_mfma_f32_32x32x16_bf16 v[4:19], v[100:103], v[96:99], v[4:19]
	v_add_f32_e32 v143, v38, v143
	v_add_f32_e32 v143, v39, v143
	v_add_f32_e32 v143, v36, v143
	v_add_f32_e32 v143, v37, v143
	v_add_f32_e32 v139, v143, v139
	s_waitcnt lgkmcnt(0)
	v_mfma_f32_32x32x16_bf16 v[20:35], v[144:147], v[96:99], v[20:35]

; __device__ __forceinline__ float fast_exp2(float x) { return __builtin_amdgcn_exp2f(x); }
; template <int D, int DV, int MODE, bool HASBIAS, bool JOINT, bool DEFER, class KA, class VA, class PF, class BF, class VF, class NM, class WS, class CB> ...
;     ...
;                     if (masked) {
; #pragma unroll
;                         for (int v = 0; v < 16; ++v) { const float p = s[v] > -1e29f ? fast_exp2(s[v] - mn) : 0.f; s[v] = p; sum += p; }
.LBB0_958:
	s_mov_b32 s10, 0xefa18f08
	v_cmp_lt_f32_e32 vcc, s10, v126
	s_nop 1
	v_cndmask_b32_e32 v48, 0, v48, vcc
	v_cmp_lt_f32_e32 vcc, s10, v127
	s_nop 1
	v_cndmask_b32_e32 v1, 0, v1, vcc
	v_cmp_lt_f32_e32 vcc, s10, v102
	s_nop 1
	v_cndmask_b32_e32 v2, 0, v2, vcc
	v_cmp_lt_f32_e32 vcc, s10, v103
	s_nop 1
	v_cndmask_b32_e32 v49, 0, v49, vcc
	v_cmp_lt_f32_e32 vcc, s10, v100
	s_nop 1
	v_cndmask_b32_e32 v46, 0, v46, vcc
	v_cmp_lt_f32_e32 vcc, s10, v101
	s_nop 1
	v_cndmask_b32_e32 v47, 0, v47, vcc
	v_cmp_lt_f32_e32 vcc, s10, v98
	s_nop 1
	v_cndmask_b32_e32 v44, 0, v44, vcc
	v_cmp_lt_f32_e32 vcc, s10, v99
	s_nop 1
	v_cndmask_b32_e32 v45, 0, v45, vcc
	v_cmp_lt_f32_e32 vcc, s10, v96
	s_nop 1
	v_cndmask_b32_e32 v42, 0, v42, vcc
	v_cmp_lt_f32_e32 vcc, s10, v97
	s_nop 1
	v_cndmask_b32_e32 v43, 0, v43, vcc
	v_cmp_lt_f32_e32 vcc, s10, v94
	s_nop 1
	v_cndmask_b32_e32 v40, 0, v40, vcc
	v_cmp_lt_f32_e32 vcc, s10, v95
	s_nop 1
	v_cndmask_b32_e32 v41, 0, v41, vcc
	v_cmp_lt_f32_e32 vcc, s10, v92
	s_nop 1
	v_cndmask_b32_e32 v38, 0, v38, vcc
	v_cmp_lt_f32_e32 vcc, s10, v93
	s_nop 1
	v_cndmask_b32_e32 v39, 0, v39, vcc
	v_cmp_lt_f32_e32 vcc, s10, v50
	s_nop 1
	v_cndmask_b32_e32 v36, 0, v36, vcc
	v_cmp_lt_f32_e32 vcc, s10, v51
	s_nop 1
	v_cndmask_b32_e32 v37, 0, v37, vcc
	s_andn2_b64 vcc, exec, s[8:9]
	s_cbranch_vccz .LBB0_910
	s_branch .LBB0_911
